# attention A loop and B far loop: cross-row max via v_permlane16_swap/v_permlane32_swap instead of ds_bpermute round trips (strategy: DPP/permlane instead of LDS)
# speedup vs baseline: 1.0027x; 1.0027x over previous
; DI unsigned pk2(float lo, float hi) { f32v2 v = {lo, hi}; bf16v2 b = __builtin_convertvector(v, bf16v2); return __builtin_bit_cast(unsigned, b); }
; template <int DQK, bool MB> ...
;     ...
;             for (int ct = 0; ct < 2; ++ct) {
;                 float mx = -INFINITY;
; #pragma unroll
;                 for (int ks = 0; ks < 4; ++ks)
; #pragma unroll
;                     for (int j = 0; j < 4; ++j) mx = fmaxf(mx, s[ks][ct][j]);
;                 mx = fmaxf(mx, __shfl_xor(mx, 16)); mx = fmaxf(mx, __shfl_xor(mx, 32));
;                 const float mnew = fmaxf(mrow[ct], mx), alpha = __builtin_amdgcn_exp2f(mrow[ct] - mnew);
;                 mrow[ct] = mnew;
;                 float ps = 0.f;
; #pragma unroll
;                 for (int ks = 0; ks < 4; ++ks)
; #pragma unroll
;                     for (int j = 0; j < 4; ++j) { const float p = __builtin_amdgcn_exp2f(s[ks][ct][j] - mnew); s[ks][ct][j] = p; ps += p; }
;                 lsum[ct] = lsum[ct] * alpha + ps; alpha2[ct] = alpha;
;             }
;             {
; #pragma unroll
;                 for (int ct = 0; ct < 2; ++ct)
; #pragma unroll
;                     for (int dt = 0; dt < 8; ++dt) o[ct][dt] *= alpha2[ct];
;             }
; #pragma unroll
;             for (int kb2 = 0; kb2 < 2; ++kb2) {
;                 bf16x8 pb[2];
; #pragma unroll
;                 for (int ct = 0; ct < 2; ++ct) { u32x4 w; w.x = pk2(s[2 * kb2][ct][0], s[2 * kb2][ct][1]); w.y = pk2(s[2 * kb2][ct][2], s[2 * kb2][ct][3]);
;                     w.z = pk2(s[2 * kb2 + 1][ct][0], s[2 * kb2 + 1][ct][1]); w.w = pk2(s[2 * kb2 + 1][ct][2], s[2 * kb2 + 1][ct][3]); pb[ct] = __builtin_bit_cast(bf16x8, w); }
.LBB0_496:
	s_nop 1
	v_max3_f32 v170, v148, s41, v149
	v_max3_f32 v170, v170, v150, v151
	v_max3_f32 v170, v170, v156, v157
	v_max3_f32 v170, v170, v158, v159
	v_max3_f32 v170, v170, v160, v161
	v_max3_f32 v170, v170, v162, v163
	v_max3_f32 v170, v170, v152, v153
	v_max3_f32 v170, v170, v154, v155
	s_mul_i32 s0, s22, 0x4400
	v_mov_b32_e32 v171, v170
	s_nop 1
	v_permlane16_swap_b32_e32 v171, v170
	v_max_f32_e32 v169, v170, v171
	v_mov_b32_e32 v170, v169
	s_nop 1
	v_permlane32_swap_b32_e32 v170, v169
	v_max3_f32 v205, v185, v169, v170
	v_sub_f32_e32 v241, v205, v185
	v_cmp_lt_f32_e64 s[98:99], 4.0, v241
	s_nop 1
	v_cndmask_b32_e64 v205, v185, v205, s[98:99]
	v_sub_f32_e32 v148, v148, v205
	v_exp_f32_e32 v169, v148
	v_sub_f32_e32 v148, v149, v205
	v_exp_f32_e32 v171, v148
	v_sub_f32_e32 v148, v150, v205
	v_exp_f32_e32 v173, v148
	v_sub_f32_e32 v148, v151, v205
	v_exp_f32_e32 v175, v148
	v_sub_f32_e32 v148, v156, v205
	v_max3_f32 v150, v136, s41, v137
	v_exp_f32_e32 v183, v148
	v_sub_f32_e32 v148, v157, v205
	v_max3_f32 v150, v150, v138, v139
	v_sub_f32_e32 v170, v185, v205
	v_exp_f32_e32 v185, v148
	v_sub_f32_e32 v148, v158, v205
	v_max3_f32 v150, v150, v144, v145
	v_exp_f32_e32 v187, v148
	v_sub_f32_e32 v148, v159, v205
	v_max3_f32 v150, v150, v146, v147
	v_exp_f32_e32 v189, v148
	v_sub_f32_e32 v148, v160, v205
	v_max3_f32 v150, v150, v132, v133
	v_exp_f32_e32 v149, v148
	v_sub_f32_e32 v148, v161, v205
	v_max3_f32 v150, v150, v134, v135
	v_exp_f32_e32 v151, v148
	v_sub_f32_e32 v148, v162, v205
	v_max3_f32 v150, v150, v140, v141
	v_exp_f32_e32 v157, v148
	v_sub_f32_e32 v148, v163, v205
	v_max3_f32 v150, v150, v142, v143
	v_exp_f32_e32 v159, v148
	v_sub_f32_e32 v148, v152, v205
	v_mov_b32_e32 v152, v150
	v_exp_f32_e32 v207, v170
	v_exp_f32_e32 v161, v148
	v_permlane16_swap_b32_e32 v152, v150
	v_sub_f32_e32 v148, v153, v205
	v_exp_f32_e32 v153, v148
	v_max_f32_e32 v150, v150, v152
	v_mov_b32_e32 v152, v150
	v_sub_f32_e32 v148, v154, v205
	v_exp_f32_e32 v163, v148
	v_permlane32_swap_b32_e32 v152, v150
	v_sub_f32_e32 v148, v155, v205
	v_exp_f32_e32 v155, v148
	v_max3_f32 v222, v184, v150, v152
	v_sub_f32_e32 v242, v222, v184
	v_cmp_lt_f32_e64 s[100:101], 4.0, v242
	s_nop 1
	v_cndmask_b32_e64 v222, v184, v222, s[100:101]
	v_sub_f32_e32 v136, v136, v222
	v_exp_f32_e32 v168, v136
	v_sub_f32_e32 v136, v137, v222
	v_exp_f32_e32 v170, v136
	v_sub_f32_e32 v136, v138, v222
	v_exp_f32_e32 v172, v136
	v_sub_f32_e32 v136, v139, v222
	v_exp_f32_e32 v174, v136
	v_sub_f32_e32 v136, v144, v222
	v_exp_f32_e32 v182, v136
	v_sub_f32_e32 v136, v145, v222
	v_sub_f32_e32 v206, v184, v222
	v_exp_f32_e32 v184, v136
	v_sub_f32_e32 v136, v146, v222
	v_exp_f32_e32 v186, v136
	v_sub_f32_e32 v136, v147, v222
	v_exp_f32_e32 v188, v136
	v_pk_add_f32 v[136:137], v[168:169], 0 op_sel_hi:[1,0]
	v_sub_f32_e32 v132, v132, v222
	v_pk_add_f32 v[136:137], v[170:171], v[136:137]
	v_exp_f32_e32 v148, v132
	v_pk_add_f32 v[136:137], v[172:173], v[136:137]
	v_sub_f32_e32 v132, v133, v222
	v_pk_add_f32 v[136:137], v[174:175], v[136:137]
	v_exp_f32_e32 v150, v132
	v_sub_f32_e32 v132, v134, v222
	v_pk_add_f32 v[136:137], v[182:183], v[136:137]
	v_exp_f32_e32 v156, v132
	v_sub_f32_e32 v132, v135, v222
	v_pk_add_f32 v[136:137], v[184:185], v[136:137]
	v_exp_f32_e32 v158, v132
	v_sub_f32_e32 v132, v140, v222
	v_pk_add_f32 v[136:137], v[186:187], v[136:137]
	v_exp_f32_e32 v160, v132
	v_sub_f32_e32 v132, v141, v222
	v_pk_add_f32 v[136:137], v[188:189], v[136:137]
	v_exp_f32_e32 v152, v132
	v_sub_f32_e32 v132, v142, v222
	v_pk_add_f32 v[136:137], v[148:149], v[136:137]
	v_exp_f32_e32 v162, v132
	v_sub_f32_e32 v132, v143, v222
	v_exp_f32_e32 v154, v132
	v_pk_add_f32 v[132:133], v[150:151], v[136:137]
	v_exp_f32_e32 v206, v206
	v_pk_add_f32 v[132:133], v[156:157], v[132:133]
	v_cvt_pk_bf16_f32 v134, v183, v185
	v_pk_add_f32 v[132:133], v[158:159], v[132:133]
	v_cvt_pk_bf16_f32 v135, v187, v189
	v_pk_add_f32 v[132:133], v[160:161], v[132:133]
	v_pk_add_f32 v[132:133], v[152:153], v[132:133]
	v_pk_add_f32 v[132:133], v[162:163], v[132:133]
	v_pk_add_f32 v[132:133], v[154:155], v[132:133]
	v_pk_fma_f32 v[180:181], v[180:181], v[206:207], v[132:133]
	v_cvt_pk_bf16_f32 v132, v169, v171
	v_add_u32_e32 v169, s0, v204
	v_cvt_pk_bf16_f32 v133, v173, v175
	v_add_u32_e32 v173, 0xc000, v169
	v_add_u32_e32 v175, 0xc800, v169
	v_add_u32_e32 v183, 0xd000, v169
	v_add_u32_e32 v185, 0xd800, v169
	v_add_u32_e32 v187, 0xe000, v169
	v_add_u32_e32 v189, 0xe800, v169
	v_add_u32_e32 v223, 0xf000, v169
	v_add_u32_e32 v225, 0xf800, v169
	s_or_b64 s[98:99], s[98:99], s[100:101]
	s_cmp_eq_u64 s[98:99], 0
	s_cbranch_scc1 .Llazy_a_skip
	v_pk_mul_f32 v[30:31], v[30:31], v[206:207] op_sel_hi:[1,0]
	v_pk_mul_f32 v[28:29], v[28:29], v[206:207] op_sel_hi:[1,0]
	v_pk_mul_f32 v[26:27], v[26:27], v[206:207] op_sel_hi:[1,0]
	v_pk_mul_f32 v[24:25], v[24:25], v[206:207] op_sel_hi:[1,0]
	v_pk_mul_f32 v[22:23], v[22:23], v[206:207] op_sel_hi:[1,0]
	v_pk_mul_f32 v[20:21], v[20:21], v[206:207] op_sel_hi:[1,0]
	v_pk_mul_f32 v[18:19], v[18:19], v[206:207] op_sel_hi:[1,0]
	v_pk_mul_f32 v[16:17], v[16:17], v[206:207] op_sel_hi:[1,0]
	v_pk_mul_f32 v[14:15], v[14:15], v[206:207] op_sel_hi:[1,0]
	v_pk_mul_f32 v[12:13], v[12:13], v[206:207] op_sel_hi:[1,0]
	v_pk_mul_f32 v[10:11], v[10:11], v[206:207] op_sel_hi:[1,0]
	v_pk_mul_f32 v[8:9], v[8:9], v[206:207] op_sel_hi:[1,0]
	v_pk_mul_f32 v[6:7], v[6:7], v[206:207] op_sel_hi:[1,0]
	v_pk_mul_f32 v[4:5], v[4:5], v[206:207] op_sel_hi:[1,0]
	v_pk_mul_f32 v[2:3], v[2:3], v[206:207] op_sel_hi:[1,0]
	v_pk_mul_f32 v[0:1], v[0:1], v[206:207] op_sel_hi:[1,0]
	v_pk_mul_f32 v[62:63], v[62:63], v[206:207] op_sel:[0,1]
	v_pk_mul_f32 v[60:61], v[60:61], v[206:207] op_sel:[0,1]
	v_pk_mul_f32 v[58:59], v[58:59], v[206:207] op_sel:[0,1]
	v_pk_mul_f32 v[56:57], v[56:57], v[206:207] op_sel:[0,1]
	v_pk_mul_f32 v[54:55], v[54:55], v[206:207] op_sel:[0,1]
	v_pk_mul_f32 v[52:53], v[52:53], v[206:207] op_sel:[0,1]
	v_pk_mul_f32 v[50:51], v[50:51], v[206:207] op_sel:[0,1]
	v_pk_mul_f32 v[48:49], v[48:49], v[206:207] op_sel:[0,1]
	v_pk_mul_f32 v[46:47], v[46:47], v[206:207] op_sel:[0,1]
	v_pk_mul_f32 v[44:45], v[44:45], v[206:207] op_sel:[0,1]
	v_pk_mul_f32 v[42:43], v[42:43], v[206:207] op_sel:[0,1]
	v_pk_mul_f32 v[40:41], v[40:41], v[206:207] op_sel:[0,1]
	v_pk_mul_f32 v[38:39], v[38:39], v[206:207] op_sel:[0,1]
	v_pk_mul_f32 v[36:37], v[36:37], v[206:207] op_sel:[0,1]
	v_pk_mul_f32 v[34:35], v[34:35], v[206:207] op_sel:[0,1]
	v_pk_mul_f32 v[32:33], v[32:33], v[206:207] op_sel:[0,1]

; #define LAS __attribute__((address_space(3)))
; template <int DQK, bool MB> ...
;     ...
;         if (act) {
;             bf16x8 kfa[KK], kfb[KK];
; #pragma unroll
;             for (int kk = 0; kk < KK; ++kk) kfa[kk] = *(const LAS bf16x8*)(kb + kk * 1024 + koff);
; #pragma unroll
;             for (int ks = 0; ks < 4; ++ks) {
;                 if (ks < 3) {
; #pragma unroll
;                     for (int kk = 0; kk < KK; ++kk) { const bf16x8 t = *(const LAS bf16x8*)(kb + ((ks + 1) * KK + kk) * 1024 + koff); if (ks & 1) kfa[kk] = t; else kfb[kk] = t; }
;                 }
;                 __builtin_amdgcn_sched_barrier(0);
;                 s[ks][0] = (f32x4){0.f, 0.f, 0.f, 0.f}; s[ks][1] = (f32x4){0.f, 0.f, 0.f, 0.f};
; #pragma unroll
;                 for (int kk = 0; kk < KK; ++kk) { const bf16x8 kf = (ks & 1) ? kfb[kk] : kfa[kk];
;                     const bf16x8 qa0 = qf[0][kk], qa1 = qf[1][kk];
;                     s[ks][0] = __builtin_amdgcn_mfma_f32_16x16x32_bf16(kf, qa0, s[ks][0], 0, 0, 0);
;                     s[ks][1] = __builtin_amdgcn_mfma_f32_16x16x32_bf16(kf, qa1, s[ks][1], 0, 0, 0); }
;                 __builtin_amdgcn_sched_barrier(0);
;             }
;         }
;         if (ST) { asm volatile("" ::: "memory"); __builtin_amdgcn_s_barrier(); asm volatile("" ::: "memory"); }
;         if (act) {
;             if (MB) {
;                 const unsigned long long mw0 = sm0[kt], mw1 = sm1[kt];
;                 if (pass == 0) {
; #pragma unroll
;                     for (int ks = 0; ks < 4; ++ks) { const unsigned b0 = (unsigned)(mw0 >> (16 * ks + 4 * q)) & 0xFu, b1 = (unsigned)(mw1 >> (16 * ks + 4 * q)) & 0xFu;
; #pragma unroll
;                         for (int j = 0; j < 4; ++j) { s[ks][0][j] = ((b0 >> j) & 1u) ? s[ks][0][j] + tbfar : -INFINITY; s[ks][1][j] = ((b1 >> j) & 1u) ? s[ks][1][j] + tbfar : -INFINITY; } }
.LBB0_665:
	v_lshl_add_u32 v156, s45, 14, v181
	ds_read_b128 v[124:127], v156
	ds_read_b128 v[128:131], v156 offset:1024
	ds_read_b128 v[132:135], v156 offset:2048
	ds_read_b128 v[136:139], v156 offset:3072
	ds_read_b128 v[140:143], v156 offset:4096
	ds_read_b128 v[160:163], v156 offset:5120
	ds_read_b128 v[164:167], v156 offset:6144
	ds_read_b128 v[186:189], v156 offset:7168
	s_waitcnt lgkmcnt(7)
	v_mfma_f32_16x16x32_bf16 v[190:193], v[124:127], v[44:47], 0
	v_mfma_f32_16x16x32_bf16 v[124:127], v[124:127], v[60:63], 0
	s_waitcnt lgkmcnt(6)
	v_mfma_f32_16x16x32_bf16 v[190:193], v[128:131], v[64:67], v[190:193]
	v_mfma_f32_16x16x32_bf16 v[124:127], v[128:131], v[72:75], v[124:127]
	s_waitcnt lgkmcnt(5)
	v_mfma_f32_16x16x32_bf16 v[128:131], v[132:135], v[68:71], v[190:193]
	v_mfma_f32_16x16x32_bf16 v[124:127], v[132:135], v[76:79], v[124:127]
	s_waitcnt lgkmcnt(4)
	v_mfma_f32_16x16x32_bf16 v[128:131], v[136:139], v[80:83], v[128:131]
	v_mfma_f32_16x16x32_bf16 v[124:127], v[136:139], v[56:59], v[124:127]
	ds_read_b128 v[132:135], v156 offset:8192
	ds_read_b128 v[136:139], v156 offset:9216
	ds_read_b128 v[190:193], v156 offset:10240
	ds_read_b128 v[194:197], v156 offset:11264
	s_waitcnt lgkmcnt(7)
	v_mfma_f32_16x16x32_bf16 v[198:201], v[140:143], v[44:47], 0
	v_mfma_f32_16x16x32_bf16 v[140:143], v[140:143], v[60:63], 0
	s_waitcnt lgkmcnt(6)
	v_mfma_f32_16x16x32_bf16 v[198:201], v[160:163], v[64:67], v[198:201]
	v_mfma_f32_16x16x32_bf16 v[140:143], v[160:163], v[72:75], v[140:143]
	s_waitcnt lgkmcnt(5)
	v_mfma_f32_16x16x32_bf16 v[160:163], v[164:167], v[68:71], v[198:201]
	v_mfma_f32_16x16x32_bf16 v[140:143], v[164:167], v[76:79], v[140:143]
	s_waitcnt lgkmcnt(4)
	v_mfma_f32_16x16x32_bf16 v[160:163], v[186:189], v[80:83], v[160:163]
	v_mfma_f32_16x16x32_bf16 v[140:143], v[186:189], v[56:59], v[140:143]
	ds_read_b128 v[164:167], v156 offset:12288
	ds_read_b128 v[186:189], v156 offset:13312
	ds_read_b128 v[198:201], v156 offset:14336
	ds_read_b128 v[202:205], v156 offset:15360
	s_waitcnt lgkmcnt(7)
	v_mfma_f32_16x16x32_bf16 v[206:209], v[132:135], v[44:47], 0
	v_mfma_f32_16x16x32_bf16 v[132:135], v[132:135], v[60:63], 0
	s_waitcnt lgkmcnt(6)
	v_mfma_f32_16x16x32_bf16 v[206:209], v[136:139], v[64:67], v[206:209]
	v_mfma_f32_16x16x32_bf16 v[132:135], v[136:139], v[72:75], v[132:135]
	s_waitcnt lgkmcnt(5)
	v_mfma_f32_16x16x32_bf16 v[136:139], v[190:193], v[68:71], v[206:209]
	v_mfma_f32_16x16x32_bf16 v[132:135], v[190:193], v[76:79], v[132:135]
	s_waitcnt lgkmcnt(4)
	v_mfma_f32_16x16x32_bf16 v[136:139], v[194:197], v[80:83], v[136:139]
	v_mfma_f32_16x16x32_bf16 v[132:135], v[194:197], v[56:59], v[132:135]
	s_waitcnt lgkmcnt(3)
	v_mfma_f32_16x16x32_bf16 v[190:193], v[164:167], v[44:47], 0
	v_mfma_f32_16x16x32_bf16 v[164:167], v[164:167], v[60:63], 0
	s_waitcnt lgkmcnt(2)
	v_mfma_f32_16x16x32_bf16 v[164:167], v[186:189], v[72:75], v[164:167]
	v_mfma_f32_16x16x32_bf16 v[190:193], v[186:189], v[64:67], v[190:193]
	s_waitcnt lgkmcnt(1)
	v_mfma_f32_16x16x32_bf16 v[164:167], v[198:201], v[76:79], v[164:167]
	v_mfma_f32_16x16x32_bf16 v[186:189], v[198:201], v[68:71], v[190:193]
	s_waitcnt lgkmcnt(0)
	v_mfma_f32_16x16x32_bf16 v[164:167], v[202:205], v[56:59], v[164:167]
	v_mfma_f32_16x16x32_bf16 v[186:189], v[202:205], v[80:83], v[186:189]
	v_mov_b32_e32 v156, s4
	s_nop 0
	ds_read2_b64 v[190:193], v156 offset1:32
	s_nop 3
	v_mov_b32_e32 v158, v164
	s_waitcnt lgkmcnt(0)
	v_lshrrev_b64 v[156:157], v150, v[192:193]
	v_bfe_i32 v243, v156, 0, 1
	v_bfe_i32 v244, v156, 1, 1
	v_bfi_b32 v168, v243, v158, v155
	v_bfe_i32 v245, v156, 2, 1
	v_bfi_b32 v169, v244, v165, v155
	v_bfe_i32 v246, v156, 3, 1
	v_bfi_b32 v166, v245, v166, v155
	s_mul_i32 s47, s45, 0x4400
	v_bfi_b32 v185, v246, v167, v155
	v_lshrrev_b64 v[156:157], v150, v[190:191]
	v_bfe_i32 v247, v156, 0, 1
	v_bfe_i32 v243, v156, 1, 1
	v_bfe_i32 v244, v156, 2, 1
	v_bfi_b32 v158, v247, v186, v155
	v_bfe_i32 v245, v156, 3, 1
	v_bfi_b32 v164, v243, v187, v155
	v_bfi_b32 v167, v244, v188, v155
	v_bfi_b32 v183, v245, v189, v155
	v_lshrrev_b64 v[156:157], v152, v[192:193]
	v_bfe_i32 v246, v156, 0, 1
	v_bfi_b32 v186, v246, v132, v155
	v_bfe_i32 v247, v156, 1, 1
	v_bfe_i32 v243, v156, 2, 1
	v_bfi_b32 v187, v247, v133, v155
	v_bfe_i32 v244, v156, 3, 1
	v_bfi_b32 v188, v243, v134, v155
	v_bfi_b32 v189, v244, v135, v155
	v_lshrrev_b64 v[132:133], v152, v[190:191]
	v_bfe_i32 v245, v132, 0, 1
	v_bfe_i32 v246, v132, 1, 1
	v_bfi_b32 v134, v245, v136, v155
	v_bfe_i32 v247, v132, 2, 1
	v_bfe_i32 v243, v132, 3, 1
	v_bfi_b32 v136, v246, v137, v155
	v_lshrrev_b32_e32 v135, v154, v192
	v_bfe_i32 v244, v135, 0, 1
	v_bfi_b32 v138, v247, v138, v155
	v_bfi_b32 v156, v243, v139, v155
	v_lshrrev_b64 v[132:133], v154, v[192:193]
	v_bfe_i32 v245, v132, 1, 1
	v_bfi_b32 v194, v244, v140, v155
	v_bfe_i32 v246, v132, 2, 1
	v_bfe_i32 v247, v132, 3, 1
	v_bfi_b32 v195, v245, v141, v155
	v_lshrrev_b32_e32 v135, v154, v190
	v_bfe_i32 v243, v135, 0, 1
	v_bfi_b32 v196, v246, v142, v155
	v_bfi_b32 v197, v247, v143, v155
	v_lshrrev_b64 v[132:133], v154, v[190:191]
	v_bfe_i32 v244, v132, 1, 1
	v_bfi_b32 v135, v243, v160, v155
	v_bfe_i32 v245, v132, 2, 1
	v_bfe_i32 v246, v132, 3, 1
	v_bfi_b32 v140, v244, v161, v155
	v_bfi_b32 v142, v245, v162, v155
	v_bfi_b32 v160, v246, v163, v155
	v_lshrrev_b64 v[132:133], v179, v[192:193]
	v_lshrrev_b32_e32 v133, v179, v192
	v_bfe_i32 v247, v133, 0, 1
	v_bfe_i32 v243, v132, 2, 1
	v_bfi_b32 v162, v247, v124, v155
	v_bfe_i32 v244, v132, 1, 1
	v_bfe_i32 v245, v132, 3, 1
	v_bfi_b32 v192, v244, v125, v155
	v_lshrrev_b64 v[124:125], v179, v[190:191]
	v_mov_b32_e32 v125, v128
	v_lshrrev_b32_e32 v128, v179, v190
; template <int DQK, bool MB> ...
;     ...
;             for (int ct = 0; ct < 2; ++ct) {
;                 float mx = -INFINITY;
; #pragma unroll
;                 for (int ks = 0; ks < 4; ++ks)
; #pragma unroll
;                     for (int j = 0; j < 4; ++j) mx = fmaxf(mx, s[ks][ct][j]);
;                 mx = fmaxf(mx, __shfl_xor(mx, 16)); mx = fmaxf(mx, __shfl_xor(mx, 32));
;                 const float mnew = fmaxf(mrow[ct], mx), alpha = __builtin_amdgcn_exp2f(mrow[ct] - mnew);
;                 mrow[ct] = mnew;
;                 float ps = 0.f;
; #pragma unroll
;                 for (int ks = 0; ks < 4; ++ks)
; #pragma unroll
;                     for (int j = 0; j < 4; ++j) { const float p = __builtin_amdgcn_exp2f(s[ks][ct][j] - mnew); s[ks][ct][j] = p; ps += p; }
;                 lsum[ct] = lsum[ct] * alpha + ps; alpha2[ct] = alpha;
;             }
;             {
; #pragma unroll
;                 for (int ct = 0; ct < 2; ++ct)
; #pragma unroll
;                     for (int dt = 0; dt < 8; ++dt) o[ct][dt] *= alpha2[ct];
	v_bfe_i32 v246, v128, 0, 1
	v_mov_b32_e32 v128, v129
	v_bfe_i32 v247, v124, 1, 1
	v_bfi_b32 v125, v246, v125, v155
	v_mov_b32_e32 v129, v130
	v_bfe_i32 v244, v124, 2, 1
	v_bfi_b32 v128, v247, v128, v155
	v_bfe_i32 v246, v124, 3, 1
	v_bfi_b32 v129, v244, v129, v155
	v_bfi_b32 v124, v246, v131, v155
	v_max3_f32 v130, v125, s79, v128
	v_max3_f32 v130, v130, v129, v124
	v_max3_f32 v130, v130, v135, v140
	v_max3_f32 v130, v130, v142, v160
	v_max3_f32 v130, v130, v134, v136
	v_max3_f32 v130, v130, v138, v156
	v_max3_f32 v130, v130, v158, v164
	v_max3_f32 v130, v130, v167, v183
	v_mov_b32_e32 v131, v130
	s_nop 1
	v_permlane16_swap_b32_e32 v131, v130
	v_max_f32_e32 v130, v130, v131
	v_mov_b32_e32 v131, v130
	v_bfi_b32 v126, v243, v126, v155
	s_nop 0
	v_permlane32_swap_b32_e32 v131, v130
	v_max_f32_e32 v182, v130, v131
	v_add_f32_e32 v182, v113, v182
	v_max_f32_e32 v182, v123, v182
	v_sub_f32_e32 v241, v182, v123
	v_cmp_lt_f32_e64 s[98:99], 4.0, v241
	s_nop 1
	v_cndmask_b32_e64 v182, v123, v182, s[98:99]
	v_sub_f32_e32 v241, v182, v113
	v_sub_f32_e32 v130, v123, v182
	v_sub_f32_e32 v123, v125, v241
	v_bfi_b32 v132, v245, v127, v155
	v_exp_f32_e32 v157, v123
	v_sub_f32_e32 v123, v128, v241
	v_max3_f32 v128, v162, s79, v192
	v_max3_f32 v128, v128, v126, v132
	v_exp_f32_e32 v143, v123
	v_sub_f32_e32 v123, v129, v241
	v_max3_f32 v128, v128, v194, v195
	v_exp_f32_e32 v141, v123
	v_sub_f32_e32 v123, v124, v241
	v_max3_f32 v128, v128, v196, v197
	v_exp_f32_e32 v139, v123
	v_sub_f32_e32 v123, v135, v241
	v_max3_f32 v128, v128, v186, v187
	v_exp_f32_e32 v137, v123
	v_sub_f32_e32 v123, v140, v241
	v_max3_f32 v128, v128, v188, v189
	v_exp_f32_e32 v135, v123
	v_sub_f32_e32 v123, v142, v241
	v_max3_f32 v128, v128, v168, v169
	v_exp_f32_e32 v133, v123
	v_sub_f32_e32 v123, v160, v241
	v_max3_f32 v128, v128, v166, v185
	v_exp_f32_e32 v131, v123
	v_sub_f32_e32 v123, v134, v241
	v_mov_b32_e32 v134, v128
	v_sub_f32_e32 v124, v158, v241
	v_exp_f32_e32 v165, v124
	v_permlane16_swap_b32_e32 v134, v128
	v_sub_f32_e32 v124, v164, v241
	v_exp_f32_e32 v161, v124
	v_max_f32_e32 v128, v128, v134
	v_mov_b32_e32 v134, v128
	v_sub_f32_e32 v124, v167, v241
	v_exp_f32_e32 v129, v123
	v_permlane32_swap_b32_e32 v134, v128
	v_sub_f32_e32 v123, v136, v241
	v_exp_f32_e32 v167, v124
	v_sub_f32_e32 v124, v183, v241
	v_max_f32_e32 v183, v128, v134
	v_add_f32_e32 v183, v113, v183
	v_max_f32_e32 v183, v122, v183
	v_sub_f32_e32 v242, v183, v122
	v_cmp_lt_f32_e64 s[100:101], 4.0, v242
	s_nop 1
	v_cndmask_b32_e64 v183, v122, v183, s[100:101]
	v_sub_f32_e32 v242, v183, v113
	v_exp_f32_e32 v127, v123
	v_sub_f32_e32 v123, v138, v241
	v_sub_f32_e32 v190, v122, v183
	v_sub_f32_e32 v122, v162, v242
	v_exp_f32_e32 v125, v123
	v_sub_f32_e32 v123, v156, v241
	v_exp_f32_e32 v156, v122
	v_sub_f32_e32 v122, v192, v242
	v_exp_f32_e32 v142, v122
	v_sub_f32_e32 v122, v126, v242
	v_exp_f32_e32 v140, v122
	v_sub_f32_e32 v122, v132, v242
	v_exp_f32_e32 v138, v122
	v_sub_f32_e32 v122, v194, v242
	v_exp_f32_e32 v136, v122
	v_sub_f32_e32 v122, v195, v242
	v_exp_f32_e32 v134, v122
	v_sub_f32_e32 v122, v196, v242
	v_sub_f32_e32 v160, v168, v242
	v_exp_f32_e32 v168, v190
	v_exp_f32_e32 v132, v122
	v_sub_f32_e32 v122, v197, v242
	v_exp_f32_e32 v158, v130
	v_exp_f32_e32 v130, v122
	v_sub_f32_e32 v122, v186, v242
	v_exp_f32_e32 v128, v122
	v_sub_f32_e32 v122, v187, v242
	v_exp_f32_e32 v126, v122
	v_sub_f32_e32 v122, v188, v242
	v_exp_f32_e32 v164, v160
	v_sub_f32_e32 v160, v169, v242
	v_sub_f32_e32 v162, v166, v242
	v_add_u32_e32 v169, s47, v180
	v_exp_f32_e32 v163, v124
	v_exp_f32_e32 v124, v122
	v_sub_f32_e32 v122, v189, v242
	v_exp_f32_e32 v166, v162
	v_sub_f32_e32 v162, v185, v242
	v_add_u32_e32 v185, 0x8000, v169
	v_add_u32_e32 v222, 0x8800, v169
	v_add_u32_e32 v223, 0x9000, v169
	v_add_u32_e32 v225, 0x9800, v169
	v_add_u32_e32 v230, 0xa000, v169
	v_add_u32_e32 v231, 0xa800, v169
	v_add_u32_e32 v232, 0xb000, v169
	v_add_u32_e32 v169, 0xb800, v169
	v_exp_f32_e32 v123, v123
	v_exp_f32_e32 v122, v122
	v_exp_f32_e32 v160, v160
	v_exp_f32_e32 v162, v162
	s_or_b64 s[98:99], s[98:99], s[100:101]
	s_cmp_eq_u64 s[98:99], 0
	s_cbranch_scc1 .Llazy_bf_skip
	v_pk_mul_f32 v[30:31], v[30:31], v[168:169] op_sel_hi:[1,0]
	v_pk_mul_f32 v[28:29], v[28:29], v[168:169] op_sel_hi:[1,0]
	v_pk_mul_f32 v[26:27], v[26:27], v[168:169] op_sel_hi:[1,0]
	v_pk_mul_f32 v[24:25], v[24:25], v[168:169] op_sel_hi:[1,0]
	v_pk_mul_f32 v[22:23], v[22:23], v[168:169] op_sel_hi:[1,0]
	v_pk_mul_f32 v[20:21], v[20:21], v[168:169] op_sel_hi:[1,0]
	v_pk_mul_f32 v[18:19], v[18:19], v[168:169] op_sel_hi:[1,0]
	v_pk_mul_f32 v[16:17], v[16:17], v[168:169] op_sel_hi:[1,0]
	v_pk_mul_f32 v[14:15], v[14:15], v[168:169] op_sel_hi:[1,0]
	v_pk_mul_f32 v[12:13], v[12:13], v[168:169] op_sel_hi:[1,0]
	v_pk_mul_f32 v[10:11], v[10:11], v[168:169] op_sel_hi:[1,0]
	v_pk_mul_f32 v[8:9], v[8:9], v[168:169] op_sel_hi:[1,0]
	v_pk_mul_f32 v[6:7], v[6:7], v[168:169] op_sel_hi:[1,0]
	v_pk_mul_f32 v[4:5], v[4:5], v[168:169] op_sel_hi:[1,0]
	v_pk_mul_f32 v[2:3], v[2:3], v[168:169] op_sel_hi:[1,0]
	v_pk_mul_f32 v[0:1], v[0:1], v[168:169] op_sel_hi:[1,0]
	v_pk_mul_f32 v[110:111], v[110:111], v[158:159] op_sel_hi:[1,0]
	v_pk_mul_f32 v[108:109], v[108:109], v[158:159] op_sel_hi:[1,0]
	v_pk_mul_f32 v[106:107], v[106:107], v[158:159] op_sel_hi:[1,0]
	v_pk_mul_f32 v[104:105], v[104:105], v[158:159] op_sel_hi:[1,0]
	v_pk_mul_f32 v[102:103], v[102:103], v[158:159] op_sel_hi:[1,0]
	v_pk_mul_f32 v[100:101], v[100:101], v[158:159] op_sel_hi:[1,0]
	v_pk_mul_f32 v[98:99], v[98:99], v[158:159] op_sel_hi:[1,0]
	v_pk_mul_f32 v[96:97], v[96:97], v[158:159] op_sel_hi:[1,0]
	v_pk_mul_f32 v[86:87], v[86:87], v[158:159] op_sel_hi:[1,0]
	v_pk_mul_f32 v[84:85], v[84:85], v[158:159] op_sel_hi:[1,0]
	v_pk_mul_f32 v[42:43], v[42:43], v[158:159] op_sel_hi:[1,0]
	v_pk_mul_f32 v[40:41], v[40:41], v[158:159] op_sel_hi:[1,0]
	v_pk_mul_f32 v[38:39], v[38:39], v[158:159] op_sel_hi:[1,0]
	v_pk_mul_f32 v[36:37], v[36:37], v[158:159] op_sel_hi:[1,0]
	v_pk_mul_f32 v[34:35], v[34:35], v[158:159] op_sel_hi:[1,0]
	v_pk_mul_f32 v[32:33], v[32:33], v[158:159] op_sel_hi:[1,0]
